# P9: second K tile's LDS-DMA issued at the tile head with the first (both LDS buffers idle there)
# speedup vs baseline: 1.0072x; 1.0072x over previous
; template <bool SWAP, class Epi>
; DI void gemm_tile(const u16* __restrict__ Ag, long lda, const u16* __restrict__ Bg, long ldb, int ka0, int ka1, int kb0, int kb1, char* shm, Epi&& epi) {
;     ...
;   auto stage = [&](int buf, int kt) {
;     char* SA = shm + buf * 32768; char* SB = SA + 16384;
; #pragma unroll
;     for (int i = 0; i < 4; ++i) {
;       const int q = i * 256 + tid, r = q >> 3, c16 = (q & 7) ^ ((r >> 1) & 7);
;       __builtin_amdgcn_global_load_lds((const unsigned*)(Ag + (long)r * lda + kt * 64 + c16 * 8), (__attribute__((address_space(3))) unsigned*)(SA + q * 16), 16, 0, 0);
;       __builtin_amdgcn_global_load_lds((const unsigned*)(Bg + (long)r * ldb + kt * 64 + c16 * 8), (__attribute__((address_space(3))) unsigned*)(SB + q * 16), 16, 0, 0);
;     }
;   };
;   stage(0, ka0 < ka1 ? ka0 : kb0);
;   for (int i = 0; i < nk; ++i) {
;     asm volatile("s_waitcnt vmcnt(0)" ::: "memory");
;     __syncthreads();
;     if (i + 1 < nk) { const int j = i + 1; stage(j & 1, j < na ? ka0 + j : kb0 + (j - na)); }
;     const char* SA = shm + (i & 1) * 32768; const char* SB = SA + 16384;
; #pragma unroll
;     for (int ks = 0; ks < 2; ++ks) {
;       bf16x8 At[4], Bt[4];
; #pragma unroll
;       for (int m = 0; m < 4; ++m) {
;         const int ra = wr * 64 + m * 16 + fr, rb = wc * 64 + m * 16 + fr;
;         At[m] = *reinterpret_cast<const bf16x8*>(SA + ra * 128 + (((ks * 4 + fq) ^ ((ra >> 1) & 7)) * 16));
;         Bt[m] = *reinterpret_cast<const bf16x8*>(SB + rb * 128 + (((ks * 4 + fq) ^ ((rb >> 1) & 7)) * 16));
;       }
; #pragma unroll
;       for (int m = 0; m < 4; ++m)
; #pragma unroll
;         for (int n = 0; n < 4; ++n) acc[m][n] = SWAP ? __builtin_amdgcn_mfma_f32_16x16x32_bf16(Bt[n], At[m], acc[m][n], 0, 0, 0) : __builtin_amdgcn_mfma_f32_16x16x32_bf16(At[m], Bt[n], acc[m][n], 0, 0, 0);
; DI void phase9(const Params& P, char* smem) {
;     ...
;   TILE_LOOP(tile, 256 * 16, 16) {
;     const int brow = (tile >> 4) * 128, hc = tile & 15;
;     gemm_tile<false>(Qp + (long)brow * 2048 + hc * 128, 2048, SKb + (long)hc * 128 * 128, 128, 0, 2, 0, 0, smem, [&](int row0, int col, f32x4 v) {
.LBB0_1125:
	v_add_u32_e32 v2, s64, v190
	v_mov_b32_e32 v22, s64
	v_cmp_gt_i32_e32 vcc, s3, v2
	v_readfirstlane_b32 s9, v25
	v_readfirstlane_b32 s16, v26
	v_cndmask_b32_e32 v2, v22, v2, vcc
	v_lshrrev_b32_e32 v22, 31, v2
	v_add_u32_e32 v22, v2, v22
	v_and_b32_e32 v23, -2, v22
	v_lshlrev_b32_e32 v22, 6, v22
	v_sub_u32_e32 v2, v2, v23
	v_and_b32_e32 v22, 0xffffff80, v22
	v_add_u32_e32 v2, s2, v2
	v_lshl_add_u32 v22, v2, 3, v22
	v_and_b32_e32 v22, 0xffffff80, v22
	v_ashrrev_i32_e32 v23, 31, v22
	v_and_b32_e32 v45, 15, v2
	v_lshlrev_b64 v[46:47], 12, v[22:23]
	v_lshlrev_b32_e32 v2, 8, v45
	v_lshl_add_u64 v[46:47], s[38:39], 0, v[46:47]
	v_lshl_add_u64 v[46:47], v[46:47], 0, v[2:3]
	v_lshlrev_b32_e32 v2, 15, v45
	v_lshl_add_u64 v[48:49], s[0:1], 0, v[2:3]
	v_lshl_add_u64 v[50:51], v[46:47], 0, v[0:1]
	v_lshl_add_u64 v[126:127], v[50:51], 0, v[18:19]
	v_lshl_add_u64 v[50:51], v[48:49], 0, v[4:5]
	s_mov_b32 m0, s9
	v_readfirstlane_b32 s17, v27
	v_lshl_add_u64 v[52:53], v[46:47], 0, v[6:7]
	global_load_lds_dwordx4 v[126:127], off
	v_lshl_add_u64 v[144:145], v[50:51], 0, v[18:19]
	s_mov_b32 m0, s16
	v_readfirstlane_b32 s18, v28
	v_lshl_add_u64 v[138:139], v[52:53], 0, v[18:19]
	v_lshl_add_u64 v[52:53], v[48:49], 0, v[8:9]
	global_load_lds_dwordx4 v[144:145], off
	s_mov_b32 m0, s17
	v_readfirstlane_b32 s19, v29
	v_lshl_add_u64 v[54:55], v[46:47], 0, v[10:11]
	v_lshl_add_u64 v[146:147], v[52:53], 0, v[18:19]
	global_load_lds_dwordx4 v[138:139], off
	s_mov_b32 m0, s18
	v_readfirstlane_b32 s20, v30
	v_lshl_add_u64 v[140:141], v[54:55], 0, v[18:19]
	v_lshl_add_u64 v[54:55], v[48:49], 0, v[12:13]
	global_load_lds_dwordx4 v[146:147], off
	s_mov_b32 m0, s19
	v_readfirstlane_b32 s21, v31
	v_lshl_add_u64 v[46:47], v[46:47], 0, v[14:15]
	v_lshl_add_u64 v[148:149], v[54:55], 0, v[18:19]
	global_load_lds_dwordx4 v[140:141], off
	s_mov_b32 m0, s20
	v_readfirstlane_b32 s22, v32
	v_lshl_add_u64 v[142:143], v[46:47], 0, v[18:19]
	v_lshl_add_u64 v[46:47], v[48:49], 0, v[16:17]
	global_load_lds_dwordx4 v[148:149], off
	s_mov_b32 m0, s21
	v_lshl_add_u64 v[150:151], v[46:47], 0, v[18:19]
	global_load_lds_dwordx4 v[142:143], off
	s_mov_b32 m0, s22
	v_readfirstlane_b32 s9, v33
	global_load_lds_dwordx4 v[150:151], off
	v_readfirstlane_b32 s16, v34
	s_mov_b32 m0, s9
	s_nop 0
	v_readfirstlane_b32 s17, v35
	v_lshl_add_u64 v[144:145], v[144:145], 0, s[6:7]
	v_readfirstlane_b32 s18, v36
	v_lshl_add_u64 v[152:153], v[140:141], 0, s[6:7]
	v_lshl_add_u64 v[154:155], v[138:139], 0, s[6:7]
	v_readfirstlane_b32 s19, v37
	v_lshl_add_u64 v[146:147], v[146:147], 0, s[6:7]
	v_readfirstlane_b32 s20, v38
	v_readfirstlane_b32 s21, v39
	v_lshl_add_u64 v[148:149], v[148:149], 0, s[6:7]
	v_readfirstlane_b32 s22, v40
	v_lshl_add_u64 v[142:143], v[142:143], 0, s[6:7]
	v_lshl_add_u64 v[114:115], v[126:127], 0, s[6:7]
	global_load_lds_dwordx4 v[114:115], off
	s_mov_b32 m0, s16
	s_nop 0
	global_load_lds_dwordx4 v[144:145], off
	s_mov_b32 m0, s17
	s_nop 0
	v_lshl_add_u64 v[126:127], v[150:151], 0, s[6:7]
	global_load_lds_dwordx4 v[154:155], off
	s_mov_b32 m0, s18
	s_nop 0
	global_load_lds_dwordx4 v[146:147], off
	s_mov_b32 m0, s19
	s_nop 0
	global_load_lds_dwordx4 v[152:153], off
	s_mov_b32 m0, s20
	s_nop 0
	global_load_lds_dwordx4 v[148:149], off
	s_mov_b32 m0, s21
	s_nop 0
	global_load_lds_dwordx4 v[142:143], off
	s_mov_b32 m0, s22
	s_nop 0
	global_load_lds_dwordx4 v[126:127], off
	s_waitcnt vmcnt(8)
	s_waitcnt vmcnt(8) lgkmcnt(0)
	s_barrier
	ds_read_b128 v[46:49], v41
	ds_read_b128 v[50:53], v42 offset:16384
	ds_read_b128 v[54:57], v41 offset:2048
	ds_read_b128 v[58:61], v42 offset:18432
	ds_read_b128 v[70:73], v42 offset:20480
	ds_read_b128 v[74:77], v42 offset:22528
	ds_read_b128 v[94:97], v41 offset:4096
	ds_read_b128 v[98:101], v41 offset:6144
	ds_read_b128 v[114:117], v43
	s_waitcnt lgkmcnt(7)
	v_mfma_f32_16x16x32_bf16 v[62:65], v[46:49], v[50:53], 0
	s_waitcnt lgkmcnt(5)
	v_mfma_f32_16x16x32_bf16 v[66:69], v[46:49], v[58:61], 0
	s_waitcnt lgkmcnt(4)
	v_mfma_f32_16x16x32_bf16 v[78:81], v[46:49], v[70:73], 0
	s_waitcnt lgkmcnt(3)
	v_mfma_f32_16x16x32_bf16 v[46:49], v[46:49], v[74:77], 0
	v_mfma_f32_16x16x32_bf16 v[82:85], v[54:57], v[50:53], 0
	v_lshl_or_b32 v2, v45, 23, v24
	v_mfma_f32_16x16x32_bf16 v[86:89], v[54:57], v[58:61], 0
	s_add_i32 s64, s64, s65
	s_cmpk_lt_i32 s64, 0x200
	v_mfma_f32_16x16x32_bf16 v[90:93], v[54:57], v[70:73], 0
	v_mfma_f32_16x16x32_bf16 v[54:57], v[54:57], v[74:77], 0
	s_waitcnt lgkmcnt(2)
	v_mfma_f32_16x16x32_bf16 v[102:105], v[94:97], v[50:53], 0
	v_mfma_f32_16x16x32_bf16 v[106:109], v[94:97], v[58:61], 0
	v_mfma_f32_16x16x32_bf16 v[110:113], v[94:97], v[70:73], 0
	v_mfma_f32_16x16x32_bf16 v[94:97], v[94:97], v[74:77], 0
	s_waitcnt lgkmcnt(1)
	v_mfma_f32_16x16x32_bf16 v[50:53], v[98:101], v[50:53], 0
	v_mfma_f32_16x16x32_bf16 v[58:61], v[98:101], v[58:61], 0
	v_mfma_f32_16x16x32_bf16 v[70:73], v[98:101], v[70:73], 0
	v_mfma_f32_16x16x32_bf16 v[74:77], v[98:101], v[74:77], 0
	ds_read_b128 v[98:101], v44 offset:16384
	ds_read_b128 v[118:121], v43 offset:2048
	ds_read_b128 v[122:125], v44 offset:18432
	ds_read_b128 v[130:133], v44 offset:20480
	ds_read_b128 v[134:137], v44 offset:22528
	s_waitcnt lgkmcnt(4)
	v_mfma_f32_16x16x32_bf16 v[62:65], v[114:117], v[98:101], v[62:65]
	s_waitcnt lgkmcnt(2)
	v_mfma_f32_16x16x32_bf16 v[66:69], v[114:117], v[122:125], v[66:69]
	s_waitcnt lgkmcnt(1)
	v_mfma_f32_16x16x32_bf16 v[78:81], v[114:117], v[130:133], v[78:81]
	s_waitcnt lgkmcnt(0)
	v_mfma_f32_16x16x32_bf16 v[46:49], v[114:117], v[134:137], v[46:49]
	ds_read_b128 v[114:117], v43 offset:4096
	ds_read_b128 v[138:141], v43 offset:6144
	v_mfma_f32_16x16x32_bf16 v[82:85], v[118:121], v[98:101], v[82:85]
	s_waitcnt lgkmcnt(0)
	v_mfma_f32_16x16x32_bf16 v[102:105], v[114:117], v[98:101], v[102:105]
	v_mfma_f32_16x16x32_bf16 v[50:53], v[138:141], v[98:101], v[50:53]
	v_mfma_f32_16x16x32_bf16 v[86:89], v[118:121], v[122:125], v[86:89]
	v_mfma_f32_16x16x32_bf16 v[90:93], v[118:121], v[130:133], v[90:93]
	s_waitcnt vmcnt(0)
	s_waitcnt vmcnt(0) lgkmcnt(0)
	s_barrier
; template <bool SWAP, class Epi>
; DI void gemm_tile(const u16* __restrict__ Ag, long lda, const u16* __restrict__ Bg, long ldb, int ka0, int ka1, int kb0, int kb1, char* shm, Epi&& epi) {
;     ...
;     const char* SA = shm + (i & 1) * 32768; const char* SB = SA + 16384;
; #pragma unroll
;     for (int ks = 0; ks < 2; ++ks) {
;       bf16x8 At[4], Bt[4];
; #pragma unroll
;       for (int m = 0; m < 4; ++m) {
;         const int ra = wr * 64 + m * 16 + fr, rb = wc * 64 + m * 16 + fr;
;         At[m] = *reinterpret_cast<const bf16x8*>(SA + ra * 128 + (((ks * 4 + fq) ^ ((ra >> 1) & 7)) * 16));
;         Bt[m] = *reinterpret_cast<const bf16x8*>(SB + rb * 128 + (((ks * 4 + fq) ^ ((rb >> 1) & 7)) * 16));
;       }
; #pragma unroll
;       for (int m = 0; m < 4; ++m)
; #pragma unroll
;         for (int n = 0; n < 4; ++n) acc[m][n] = SWAP ? __builtin_amdgcn_mfma_f32_16x16x32_bf16(Bt[n], At[m], acc[m][n], 0, 0, 0) : __builtin_amdgcn_mfma_f32_16x16x32_bf16(At[m], Bt[n], acc[m][n], 0, 0, 0);
;     }
;   }
;   __syncthreads();
; #pragma unroll
;   for (int m = 0; m < 4; ++m)
; #pragma unroll
;     for (int n = 0; n < 4; ++n) { if (SWAP) epi(wr * 64 + m * 16 + fr, wc * 64 + n * 16 + fq * 4, acc[m][n]); else epi(wr * 64 + m * 16 + fq * 4, wc * 64 + n * 16 + fr, acc[m][n]); }
; DI void phase9(const Params& P, char* smem) {
;     ...
;     gemm_tile<false>(Qp + (long)brow * 2048 + hc * 128, 2048, SKb + (long)hc * 128 * 128, 128, 0, 2, 0, 0, smem, [&](int row0, int col, f32x4 v) {
;       typedef _Float16 h4 __attribute__((ext_vector_type(4)));
;       h4 hv; hv[0] = (_Float16)v[0]; hv[1] = (_Float16)v[1]; hv[2] = (_Float16)v[2]; hv[3] = (_Float16)v[3];
;       *reinterpret_cast<h4*>(ST + ((long)(hc * 128 + col)) * NTOK + brow + row0) = hv;
;     });
	ds_read_b128 v[98:101], v41 offset:32768
	v_mfma_f32_16x16x32_bf16 v[54:57], v[118:121], v[134:137], v[54:57]
	ds_read_b128 v[118:121], v42 offset:51200
	v_lshl_add_u64 v[126:127], s[40:41], 0, v[2:3]
	v_lshl_add_u64 v[22:23], v[22:23], 1, v[126:127]
	v_mfma_f32_16x16x32_bf16 v[106:109], v[114:117], v[122:125], v[106:109]
	v_lshl_add_u64 v[22:23], v[22:23], 0, v[20:21]
	v_lshl_add_u64 v[126:127], v[22:23], 0, s[10:11]
	v_mfma_f32_16x16x32_bf16 v[110:113], v[114:117], v[130:133], v[110:113]
	v_mfma_f32_16x16x32_bf16 v[94:97], v[114:117], v[134:137], v[94:97]
	ds_read_b128 v[114:117], v42 offset:49152
	v_mfma_f32_16x16x32_bf16 v[58:61], v[138:141], v[122:125], v[58:61]
	ds_read_b128 v[122:125], v42 offset:53248
	v_mfma_f32_16x16x32_bf16 v[70:73], v[138:141], v[130:133], v[70:73]
	ds_read_b128 v[130:133], v42 offset:55296
	s_waitcnt lgkmcnt(2)
	v_mfma_f32_16x16x32_bf16 v[62:65], v[98:101], v[114:117], v[62:65]
	v_mfma_f32_16x16x32_bf16 v[66:69], v[98:101], v[118:121], v[66:69]
	s_waitcnt lgkmcnt(1)
	v_mfma_f32_16x16x32_bf16 v[78:81], v[98:101], v[122:125], v[78:81]
	s_waitcnt lgkmcnt(0)
	v_mfma_f32_16x16x32_bf16 v[46:49], v[98:101], v[130:133], v[46:49]
	ds_read_b128 v[98:101], v41 offset:34816
	s_waitcnt lgkmcnt(0)
	v_mfma_f32_16x16x32_bf16 v[82:85], v[98:101], v[114:117], v[82:85]
	v_mfma_f32_16x16x32_bf16 v[86:89], v[98:101], v[118:121], v[86:89]
	v_mfma_f32_16x16x32_bf16 v[90:93], v[98:101], v[122:125], v[90:93]
	v_mfma_f32_16x16x32_bf16 v[54:57], v[98:101], v[130:133], v[54:57]
	ds_read_b128 v[98:101], v41 offset:36864
	s_waitcnt lgkmcnt(0)
	v_mfma_f32_16x16x32_bf16 v[102:105], v[98:101], v[114:117], v[102:105]
	v_mfma_f32_16x16x32_bf16 v[106:109], v[98:101], v[118:121], v[106:109]
	v_mfma_f32_16x16x32_bf16 v[110:113], v[98:101], v[122:125], v[110:113]
	v_mfma_f32_16x16x32_bf16 v[94:97], v[98:101], v[130:133], v[94:97]
	ds_read_b128 v[98:101], v41 offset:38912
	v_mfma_f32_16x16x32_bf16 v[74:77], v[138:141], v[134:137], v[74:77]
	v_add_co_u32_e32 v134, vcc, s4, v22
	v_lshl_add_u64 v[136:137], v[22:23], 0, s[12:13]
	s_waitcnt lgkmcnt(0)
	v_mfma_f32_16x16x32_bf16 v[50:53], v[98:101], v[114:117], v[50:53]
	ds_read_b128 v[114:117], v43 offset:32768
	v_addc_co_u32_e32 v135, vcc, 0, v23, vcc
	v_mfma_f32_16x16x32_bf16 v[58:61], v[98:101], v[118:121], v[58:61]
	ds_read_b128 v[118:121], v44 offset:51200
	v_add_co_u32_e32 v138, vcc, s5, v22
	v_mfma_f32_16x16x32_bf16 v[70:73], v[98:101], v[122:125], v[70:73]
	ds_read_b128 v[122:125], v44 offset:53248
	v_addc_co_u32_e32 v139, vcc, 0, v23, vcc
	v_mfma_f32_16x16x32_bf16 v[74:77], v[98:101], v[130:133], v[74:77]
	ds_read_b128 v[98:101], v44 offset:49152
	ds_read_b128 v[130:133], v44 offset:55296
	s_waitcnt lgkmcnt(1)
	v_mfma_f32_16x16x32_bf16 v[62:65], v[114:117], v[98:101], v[62:65]
	v_mfma_f32_16x16x32_bf16 v[66:69], v[114:117], v[118:121], v[66:69]
	s_nop 6
	v_cvt_pk_f16_f32 v65, v64, v65
	v_cvt_pk_f16_f32 v64, v62, v63
	v_mfma_f32_16x16x32_bf16 v[78:81], v[114:117], v[122:125], v[78:81]
	s_waitcnt lgkmcnt(0)
	v_mfma_f32_16x16x32_bf16 v[46:49], v[114:117], v[130:133], v[46:49]
	ds_read_b128 v[114:117], v43 offset:34816
	v_cvt_pk_f16_f32 v63, v68, v69
	v_cvt_pk_f16_f32 v62, v66, v67
	s_waitcnt lgkmcnt(0)
	v_mfma_f32_16x16x32_bf16 v[82:85], v[114:117], v[98:101], v[82:85]
	s_nop 0
	v_cvt_pk_f16_f32 v67, v80, v81
	v_cvt_pk_f16_f32 v66, v78, v79
	v_cvt_pk_f16_f32 v49, v48, v49
	v_mfma_f32_16x16x32_bf16 v[86:89], v[114:117], v[118:121], v[86:89]
	v_cvt_pk_f16_f32 v48, v46, v47
	s_nop 1
	v_cvt_pk_f16_f32 v47, v84, v85
	v_cvt_pk_f16_f32 v46, v82, v83
	v_mfma_f32_16x16x32_bf16 v[90:93], v[114:117], v[122:125], v[90:93]
	v_mfma_f32_16x16x32_bf16 v[54:57], v[114:117], v[130:133], v[54:57]
	ds_read_b128 v[114:117], v43 offset:36864
	v_cvt_pk_f16_f32 v69, v88, v89
	v_cvt_pk_f16_f32 v68, v86, v87
	s_waitcnt lgkmcnt(0)
	v_mfma_f32_16x16x32_bf16 v[102:105], v[114:117], v[98:101], v[102:105]
	s_nop 1
	v_cvt_pk_f16_f32 v79, v92, v93
	v_cvt_pk_f16_f32 v78, v90, v91
	v_cvt_pk_f16_f32 v57, v56, v57
	v_mfma_f32_16x16x32_bf16 v[106:109], v[114:117], v[118:121], v[106:109]
	v_cvt_pk_f16_f32 v56, v54, v55
	s_nop 0
	v_cvt_pk_f16_f32 v55, v104, v105
	v_cvt_pk_f16_f32 v54, v102, v103
	v_mfma_f32_16x16x32_bf16 v[110:113], v[114:117], v[122:125], v[110:113]
	v_mfma_f32_16x16x32_bf16 v[94:97], v[114:117], v[130:133], v[94:97]
	ds_read_b128 v[114:117], v43 offset:38912
	s_waitcnt lgkmcnt(0)
	s_barrier
	v_mfma_f32_16x16x32_bf16 v[50:53], v[114:117], v[98:101], v[50:53]
	v_add_co_u32_e32 v100, vcc, s8, v22
	v_lshl_add_u64 v[98:99], v[22:23], 0, s[14:15]
	v_mfma_f32_16x16x32_bf16 v[58:61], v[114:117], v[118:121], v[58:61]
	v_addc_co_u32_e32 v101, vcc, 0, v23, vcc
	v_mfma_f32_16x16x32_bf16 v[70:73], v[114:117], v[122:125], v[70:73]
	v_cvt_pk_f16_f32 v81, v108, v109
	v_cvt_pk_f16_f32 v80, v106, v107
	v_cvt_pk_f16_f32 v83, v112, v113
	v_mfma_f32_16x16x32_bf16 v[74:77], v[114:117], v[130:133], v[74:77]
	v_cvt_pk_f16_f32 v82, v110, v111
	v_cvt_pk_f16_f32 v85, v96, v97
	v_cvt_pk_f16_f32 v84, v94, v95
	v_cvt_pk_f16_f32 v53, v52, v53
	v_cvt_pk_f16_f32 v52, v50, v51
	v_cvt_pk_f16_f32 v51, v60, v61
	v_cvt_pk_f16_f32 v50, v58, v59
	v_cvt_pk_f16_f32 v59, v72, v73
	v_cvt_pk_f16_f32 v58, v70, v71
	v_cvt_pk_f16_f32 v61, v76, v77
	v_cvt_pk_f16_f32 v60, v74, v75
	global_store_dwordx2 v[22:23], v[64:65], off
	global_store_dwordx2 v[134:135], v[62:63], off
	global_store_dwordx2 v[138:139], v[66:67], off
	global_store_dwordx2 v[100:101], v[48:49], off
	global_store_dwordx2 v[22:23], v[46:47], off offset:32
	global_store_dwordx2 v[126:127], v[68:69], off offset:32
	global_store_dwordx2 v[136:137], v[78:79], off offset:32
	global_store_dwordx2 v[98:99], v[56:57], off offset:32
	global_store_dwordx2 v[22:23], v[54:55], off offset:64
	global_store_dwordx2 v[126:127], v[80:81], off offset:64
	global_store_dwordx2 v[136:137], v[82:83], off offset:64
	global_store_dwordx2 v[98:99], v[84:85], off offset:64
	global_store_dwordx2 v[22:23], v[52:53], off offset:96
	global_store_dwordx2 v[126:127], v[50:51], off offset:96
	global_store_dwordx2 v[136:137], v[58:59], off offset:96
	global_store_dwordx2 v[98:99], v[60:61], off offset:96
	s_cbranch_scc1 .LBB0_1125
